# stack + MoBA loop: next key tile's K fragments read from LDS under the current tile's last PV MFMAs / row-sum adds (dead registers v136-159)
# speedup vs baseline: 1.0000x; 1.0000x over previous
.LBB0_392:
	s_nop 10
	v_max3_f32 v24, v0, s38, v1
	v_max3_f32 v24, v24, v2, v3
	v_max3_f32 v24, v24, v4, v5
	v_max3_f32 v24, v24, v6, v7
	v_max3_f32 v24, v24, v8, v9
	v_max3_f32 v24, v24, v10, v11
	v_max3_f32 v24, v24, v12, v13
	v_max3_f32 v24, v24, v14, v15
	v_max3_f32 v24, v24, v32, v33
	v_max3_f32 v24, v24, v34, v35
	v_max3_f32 v24, v24, v36, v37
	v_max3_f32 v24, v24, v38, v39
	v_max3_f32 v24, v24, v40, v41
	v_max3_f32 v24, v24, v42, v43
	v_max3_f32 v24, v24, v44, v45
	v_max3_f32 v24, v24, v46, v47
	ds_bpermute_b32 v25, v238, v24
	s_and_b64 vcc, s[0:1], exec
	s_cselect_b32 s58, s58, 0x63
	s_cmp_lt_u32 s58, 2
	s_waitcnt lgkmcnt(0)
	v_max3_f32 v197, v24, v25, s38
	v_sub_f32_e32 v0, v0, v197
	v_exp_f32_e32 v141, v0
	v_sub_f32_e32 v0, v1, v197
	v_exp_f32_e32 v142, v0
	v_sub_f32_e32 v0, v2, v197
	v_exp_f32_e32 v143, v0
	v_sub_f32_e32 v0, v3, v197
	v_exp_f32_e32 v144, v0
	v_sub_f32_e32 v0, v4, v197
	v_exp_f32_e32 v145, v0
	v_sub_f32_e32 v0, v5, v197
	v_exp_f32_e32 v146, v0
	v_sub_f32_e32 v0, v6, v197
	v_exp_f32_e32 v147, v0
	v_sub_f32_e32 v0, v7, v197
	v_exp_f32_e32 v148, v0
	v_sub_f32_e32 v0, v8, v197
	v_exp_f32_e32 v149, v0
	v_sub_f32_e32 v0, v9, v197
	v_exp_f32_e32 v150, v0
	v_sub_f32_e32 v0, v10, v197
	v_exp_f32_e32 v151, v0
	v_sub_f32_e32 v0, v11, v197
	v_exp_f32_e32 v152, v0
	v_sub_f32_e32 v0, v12, v197
	v_exp_f32_e32 v153, v0
	v_sub_f32_e32 v0, v13, v197
	v_sub_f32_e32 v24, 0xff800000, v197
	v_exp_f32_e32 v154, v0
	v_sub_f32_e32 v0, v14, v197
	v_exp_f32_e32 v140, v24
	v_exp_f32_e32 v155, v0
	v_sub_f32_e32 v0, v15, v197
	v_cvt_pk_bf16_f32 v24, v141, v142
	v_cvt_pk_bf16_f32 v25, v143, v144
	v_cvt_pk_bf16_f32 v26, v145, v146
	v_cvt_pk_bf16_f32 v27, v147, v148
	v_exp_f32_e32 v156, v0
	v_cvt_pk_bf16_f32 v136, v149, v150
	v_mfma_f32_32x32x16_bf16 v[0:15], v[20:23], v[24:27], 0
	v_cvt_pk_bf16_f32 v137, v151, v152
	v_cvt_pk_bf16_f32 v138, v153, v154
	v_cvt_pk_bf16_f32 v139, v155, v156
	v_sub_f32_e32 v32, v32, v197
	v_fmac_f32_e32 v141, 0, v140
	v_mfma_f32_32x32x16_bf16 v[16:31], v[16:19], v[24:27], 0
	v_mfma_f32_32x32x16_bf16 v[16:31], v[128:131], v[136:139], v[16:31]
	v_exp_f32_e32 v129, v32
	v_sub_f32_e32 v32, v33, v197
	v_exp_f32_e32 v130, v32
	v_sub_f32_e32 v32, v34, v197
	v_exp_f32_e32 v131, v32
	v_sub_f32_e32 v32, v35, v197
	v_add_f32_e32 v128, v142, v141
	v_mfma_f32_32x32x16_bf16 v[0:15], v[132:135], v[136:139], v[0:15]
	v_exp_f32_e32 v132, v32
	v_sub_f32_e32 v32, v36, v197
	v_exp_f32_e32 v36, v32
	v_sub_f32_e32 v32, v37, v197
	v_exp_f32_e32 v37, v32
	v_sub_f32_e32 v32, v38, v197
	v_exp_f32_e32 v38, v32
	v_sub_f32_e32 v32, v39, v197
	v_exp_f32_e32 v39, v32
	v_sub_f32_e32 v32, v40, v197
	v_exp_f32_e32 v40, v32
	v_sub_f32_e32 v32, v41, v197
	v_exp_f32_e32 v41, v32
	v_sub_f32_e32 v32, v42, v197
	v_add_f32_e32 v128, v143, v128
	v_exp_f32_e32 v42, v32
	v_sub_f32_e32 v32, v43, v197
	v_add_f32_e32 v128, v144, v128
	v_exp_f32_e32 v43, v32
	v_sub_f32_e32 v32, v44, v197
	v_add_f32_e32 v128, v145, v128
	v_exp_f32_e32 v44, v32
	v_sub_f32_e32 v32, v45, v197
	v_add_f32_e32 v128, v146, v128
	v_exp_f32_e32 v45, v32
	v_sub_f32_e32 v32, v46, v197
	v_add_f32_e32 v128, v147, v128
	v_exp_f32_e32 v46, v32
	v_sub_f32_e32 v32, v47, v197
	v_add_f32_e32 v128, v148, v128
	v_exp_f32_e32 v47, v32
	v_cvt_pk_bf16_f32 v32, v129, v130
	v_cvt_pk_bf16_f32 v33, v131, v132
	v_cvt_pk_bf16_f32 v34, v36, v37
	v_cvt_pk_bf16_f32 v35, v38, v39
	v_add_f32_e32 v128, v149, v128
	v_add_f32_e32 v128, v150, v128
	v_mfma_f32_32x32x16_bf16 v[0:15], v[60:63], v[32:35], v[0:15]
	v_add_f32_e32 v128, v151, v128
	v_add_f32_e32 v128, v152, v128
	v_add_f32_e32 v128, v153, v128
	v_add_f32_e32 v128, v154, v128
	v_add_f32_e32 v128, v155, v128
	v_add_f32_e32 v128, v156, v128
	v_mfma_f32_32x32x16_bf16 v[16:31], v[56:59], v[32:35], v[16:31]
	ds_read_b128 v[152:155], v233 offset:9216
	ds_read_b128 v[156:159], v233 offset:13824
	ds_read_b128 v[140:143], v233 offset:13856
	ds_read_b128 v[144:147], v233 offset:13888
	ds_read_b128 v[136:139], v233 offset:9312
	ds_read_b128 v[148:151], v233 offset:13920
	v_cvt_pk_bf16_f32 v32, v40, v41
	v_cvt_pk_bf16_f32 v33, v42, v43
	v_cvt_pk_bf16_f32 v34, v44, v45
	v_cvt_pk_bf16_f32 v35, v46, v47
	s_nop 1
	v_mfma_f32_32x32x16_bf16 v[0:15], v[52:55], v[32:35], v[0:15]
	v_mfma_f32_32x32x16_bf16 v[16:31], v[48:51], v[32:35], v[16:31]
	v_add_f32_e32 v32, v129, v128
	v_add_f32_e32 v32, v130, v32
	v_add_f32_e32 v32, v131, v32
	v_add_f32_e32 v32, v132, v32
	v_add_f32_e32 v32, v36, v32
	v_add_f32_e32 v32, v37, v32
	v_add_f32_e32 v32, v38, v32
	v_add_f32_e32 v32, v39, v32
	v_add_f32_e32 v32, v40, v32
	v_add_f32_e32 v32, v41, v32
	v_add_f32_e32 v32, v42, v32
	v_add_f32_e32 v32, v43, v32
	v_add_f32_e32 v32, v44, v32
	v_add_f32_e32 v32, v45, v32
	v_add_f32_e32 v32, v46, v32
	v_add_f32_e32 v162, v47, v32
	v_cndmask_b32_e64 v32, 0, 1, s[0:1]
	v_cmp_ne_u32_e64 s[0:1], 1, v32
	s_cbranch_scc1 .LBB0_397
	ds_read_b128 v[128:131], v233 offset:9248
	ds_read_b128 v[132:135], v233 offset:9280
	s_waitcnt lgkmcnt(2)
	v_mfma_f32_32x32x16_bf16 v[48:63], v[152:155], v[108:111], 0
	s_and_b64 vcc, exec, s[0:1]
	v_mfma_f32_32x32x16_bf16 v[32:47], v[156:159], v[108:111], 0
	s_waitcnt lgkmcnt(1)
	v_mfma_f32_32x32x16_bf16 v[48:63], v[128:131], v[104:107], v[48:63]
	v_mfma_f32_32x32x16_bf16 v[32:47], v[140:143], v[104:107], v[32:47]
	s_waitcnt lgkmcnt(0)
	v_mfma_f32_32x32x16_bf16 v[48:63], v[132:135], v[100:103], v[48:63]
	v_mfma_f32_32x32x16_bf16 v[32:47], v[144:147], v[100:103], v[32:47]
	v_mfma_f32_32x32x16_bf16 v[48:63], v[136:139], v[96:99], v[48:63]
	v_mfma_f32_32x32x16_bf16 v[32:47], v[148:151], v[96:99], v[32:47]
	ds_read_b128 v[156:159], v234 offset:36992
	ds_read_b128 v[144:147], v234 offset:37024
	ds_read_b128 v[152:155], v234 offset:53888
	ds_read_b128 v[148:151], v234 offset:53920
	ds_read_b128 v[140:143], v234 offset:37056
	ds_read_b128 v[136:139], v234 offset:53952
	ds_read_b128 v[132:135], v234 offset:37088
	ds_read_b128 v[128:131], v234 offset:53984
	s_cbranch_vccnz .LBB0_395
	v_add_u32_e32 v244, s88, v240
	v_subrev_u32_e32 v245, 64, v244
	v_cmp_gt_i32_e32 vcc, v203, v245
	v_add_u32_e32 v244, 0xffffffa0, v244
	s_nop 0
	v_cndmask_b32_e32 v246, v48, v235, vcc
	v_cmp_lt_i32_e32 vcc, v203, v245
	s_nop 1
	v_cndmask_b32_e32 v48, v246, v48, vcc
	v_cndmask_b32_e32 v49, v235, v49, vcc
	v_cmp_le_i32_e32 vcc, v204, v245
	s_nop 1
	v_cndmask_b32_e32 v50, v235, v50, vcc
	v_cmp_le_i32_e32 vcc, v205, v245
	s_nop 1
	v_cndmask_b32_e32 v51, v235, v51, vcc
	v_cmp_le_i32_e32 vcc, v206, v245
	s_nop 1
	v_cndmask_b32_e32 v52, v235, v52, vcc
	v_cmp_le_i32_e32 vcc, v207, v245
	s_nop 1
	v_cndmask_b32_e32 v53, v235, v53, vcc
	v_cmp_le_i32_e32 vcc, v208, v245
	s_nop 1
	v_cndmask_b32_e32 v54, v235, v54, vcc
	v_cmp_le_i32_e32 vcc, v209, v245
	s_nop 1
	v_cndmask_b32_e32 v55, v235, v55, vcc
	v_cmp_le_i32_e32 vcc, v210, v245
	s_nop 1
	v_cndmask_b32_e32 v56, v235, v56, vcc
	v_cmp_le_i32_e32 vcc, v211, v245
	s_nop 1
	v_cndmask_b32_e32 v57, v235, v57, vcc
	v_cmp_le_i32_e32 vcc, v212, v245
	s_nop 1
	v_cndmask_b32_e32 v58, v235, v58, vcc
	v_cmp_le_i32_e32 vcc, v213, v245
	s_nop 1
	v_cndmask_b32_e32 v59, v235, v59, vcc
	v_cmp_le_i32_e32 vcc, v214, v245
	s_nop 1
	v_cndmask_b32_e32 v60, v235, v60, vcc
	v_cmp_le_i32_e32 vcc, v216, v245
	s_nop 1
	v_cndmask_b32_e32 v61, v235, v61, vcc
	v_cmp_le_i32_e32 vcc, v217, v245
	s_nop 1
	v_cndmask_b32_e32 v62, v235, v62, vcc
	v_cmp_le_i32_e32 vcc, v218, v245
	s_nop 1
	v_cndmask_b32_e32 v63, v235, v63, vcc
	v_cmp_le_i32_e32 vcc, v203, v244
	s_nop 1
	v_cndmask_b32_e32 v32, v235, v32, vcc
	v_cmp_lt_i32_e32 vcc, v203, v244
	s_nop 1
	v_cndmask_b32_e32 v33, v235, v33, vcc
	v_cmp_le_i32_e32 vcc, v204, v244
	s_nop 1
	v_cndmask_b32_e32 v34, v235, v34, vcc
	v_cmp_le_i32_e32 vcc, v205, v244
	s_nop 1
	v_cndmask_b32_e32 v35, v235, v35, vcc
	v_cmp_le_i32_e32 vcc, v206, v244
	s_nop 1
	v_cndmask_b32_e32 v36, v235, v36, vcc
	v_cmp_le_i32_e32 vcc, v207, v244
	s_nop 1
	v_cndmask_b32_e32 v37, v235, v37, vcc
	v_cmp_le_i32_e32 vcc, v208, v244
	s_nop 1
	v_cndmask_b32_e32 v38, v235, v38, vcc
	v_cmp_le_i32_e32 vcc, v209, v244
	s_nop 1
	v_cndmask_b32_e32 v39, v235, v39, vcc
	v_cmp_le_i32_e32 vcc, v210, v244
	s_nop 1
	v_cndmask_b32_e32 v40, v235, v40, vcc
	v_cmp_le_i32_e32 vcc, v211, v244
	s_nop 1
	v_cndmask_b32_e32 v41, v235, v41, vcc
	v_cmp_le_i32_e32 vcc, v212, v244
	s_nop 1
	v_cndmask_b32_e32 v42, v235, v42, vcc
	v_cmp_le_i32_e32 vcc, v213, v244
	s_nop 1
	v_cndmask_b32_e32 v43, v235, v43, vcc
	v_cmp_le_i32_e32 vcc, v214, v244
	s_nop 1
	v_cndmask_b32_e32 v44, v235, v44, vcc
	v_cmp_le_i32_e32 vcc, v216, v244
	s_nop 1
	v_cndmask_b32_e32 v45, v235, v45, vcc
	v_cmp_le_i32_e32 vcc, v217, v244
	s_nop 1
	v_cndmask_b32_e32 v46, v235, v46, vcc
	v_cmp_le_i32_e32 vcc, v218, v244
	s_nop 1
	v_cndmask_b32_e32 v47, v235, v47, vcc

.Lp3lz_skip2:
	s_nop 1
	v_mfma_f32_32x32x16_bf16 v[0:15], v[156:159], v[48:51], v[0:15]
	v_fmac_f32_e32 v197, v162, v244
	v_sub_f32_e32 v32, v32, v245
	v_mfma_f32_32x32x16_bf16 v[16:31], v[152:155], v[48:51], v[16:31]
	v_cvt_pk_bf16_f32 v48, v56, v57
	v_cvt_pk_bf16_f32 v49, v58, v59
	v_cvt_pk_bf16_f32 v50, v60, v61
	v_cvt_pk_bf16_f32 v51, v62, v63
	s_nop 1
	v_mfma_f32_32x32x16_bf16 v[0:15], v[144:147], v[48:51], v[0:15]
	v_mfma_f32_32x32x16_bf16 v[16:31], v[148:151], v[48:51], v[16:31]
	v_add_f32_e32 v48, v246, v197
	v_exp_f32_e32 v49, v32
	v_sub_f32_e32 v32, v33, v245
	v_add_f32_e32 v48, v247, v48
	v_exp_f32_e32 v50, v32
	v_sub_f32_e32 v32, v34, v245
	v_add_f32_e32 v48, v248, v48
	v_exp_f32_e32 v51, v32
	v_sub_f32_e32 v32, v35, v245
	v_add_f32_e32 v48, v52, v48
	v_exp_f32_e32 v52, v32
	v_sub_f32_e32 v32, v36, v245
	v_exp_f32_e32 v36, v32
	v_sub_f32_e32 v32, v37, v245
	v_exp_f32_e32 v37, v32
	v_sub_f32_e32 v32, v38, v245
	v_exp_f32_e32 v38, v32
	v_sub_f32_e32 v32, v39, v245
	v_exp_f32_e32 v39, v32
	v_sub_f32_e32 v32, v40, v245
	v_exp_f32_e32 v40, v32
	v_sub_f32_e32 v32, v41, v245
	v_exp_f32_e32 v41, v32
	v_sub_f32_e32 v32, v42, v245
	v_exp_f32_e32 v42, v32
	v_sub_f32_e32 v32, v43, v245
	v_exp_f32_e32 v43, v32
	v_sub_f32_e32 v32, v44, v245
	v_exp_f32_e32 v44, v32
	v_sub_f32_e32 v32, v45, v245
	v_add_f32_e32 v48, v53, v48
	v_exp_f32_e32 v45, v32
	v_sub_f32_e32 v32, v46, v245
	v_add_f32_e32 v48, v54, v48
	v_exp_f32_e32 v46, v32
	v_sub_f32_e32 v32, v47, v245
	v_add_f32_e32 v48, v55, v48
	v_exp_f32_e32 v47, v32
	v_cvt_pk_bf16_f32 v32, v49, v50
	v_cvt_pk_bf16_f32 v33, v51, v52
	v_cvt_pk_bf16_f32 v34, v36, v37
	v_cvt_pk_bf16_f32 v35, v38, v39
	v_add_f32_e32 v48, v56, v48
	v_add_f32_e32 v48, v57, v48
	v_mfma_f32_32x32x16_bf16 v[0:15], v[140:143], v[32:35], v[0:15]
	v_add_f32_e32 v48, v58, v48
	v_add_f32_e32 v48, v59, v48
	v_add_f32_e32 v48, v60, v48
	v_add_f32_e32 v48, v61, v48
	v_add_f32_e32 v48, v62, v48
	v_add_f32_e32 v48, v63, v48
	v_mov_b32_e32 v197, v245
	v_mfma_f32_32x32x16_bf16 v[16:31], v[136:139], v[32:35], v[16:31]
	ds_read_b128 v[152:155], v233 offset:18432
	ds_read_b128 v[156:159], v233 offset:23040
	ds_read_b128 v[140:143], v233 offset:23072
	ds_read_b128 v[144:147], v233 offset:23104
	ds_read_b128 v[136:139], v233 offset:18528
	ds_read_b128 v[148:151], v233 offset:23136
	v_cvt_pk_bf16_f32 v32, v40, v41
	v_cvt_pk_bf16_f32 v33, v42, v43
	v_cvt_pk_bf16_f32 v34, v44, v45
	v_cvt_pk_bf16_f32 v35, v46, v47
	s_nop 1
	v_mfma_f32_32x32x16_bf16 v[0:15], v[132:135], v[32:35], v[0:15]
	v_mfma_f32_32x32x16_bf16 v[16:31], v[128:131], v[32:35], v[16:31]
	v_add_f32_e32 v32, v49, v48
	v_add_f32_e32 v32, v50, v32
	v_add_f32_e32 v32, v51, v32
	v_add_f32_e32 v32, v52, v32
	v_add_f32_e32 v32, v36, v32
	v_add_f32_e32 v32, v37, v32
	v_add_f32_e32 v32, v38, v32
	v_add_f32_e32 v32, v39, v32
	v_add_f32_e32 v32, v40, v32
	v_add_f32_e32 v32, v41, v32
	v_add_f32_e32 v32, v42, v32
	v_add_f32_e32 v32, v43, v32
	v_add_f32_e32 v32, v44, v32
	v_add_f32_e32 v32, v45, v32
	v_add_f32_e32 v32, v46, v32
	v_add_f32_e32 v162, v47, v32
	s_cmp_lt_u32 s58, 4
	s_cbranch_scc0 .LBB0_398

.LBB0_398:
	ds_read_b128 v[128:131], v233 offset:18464
	ds_read_b128 v[132:135], v233 offset:18496
	s_waitcnt lgkmcnt(2)
	v_mfma_f32_32x32x16_bf16 v[48:63], v[152:155], v[108:111], 0
	s_and_b64 vcc, exec, s[0:1]
	v_mfma_f32_32x32x16_bf16 v[32:47], v[156:159], v[108:111], 0
	s_waitcnt lgkmcnt(1)
	v_mfma_f32_32x32x16_bf16 v[48:63], v[128:131], v[104:107], v[48:63]
	v_mfma_f32_32x32x16_bf16 v[32:47], v[140:143], v[104:107], v[32:47]
	s_waitcnt lgkmcnt(0)
	v_mfma_f32_32x32x16_bf16 v[48:63], v[132:135], v[100:103], v[48:63]
	v_mfma_f32_32x32x16_bf16 v[32:47], v[144:147], v[100:103], v[32:47]
	v_mfma_f32_32x32x16_bf16 v[48:63], v[136:139], v[96:99], v[48:63]
	v_mfma_f32_32x32x16_bf16 v[32:47], v[148:151], v[96:99], v[32:47]
	ds_read_b128 v[156:159], v234 offset:37120
	ds_read_b128 v[144:147], v234 offset:37152
	ds_read_b128 v[152:155], v234 offset:54016
	ds_read_b128 v[148:151], v234 offset:54048
	ds_read_b128 v[140:143], v234 offset:37184
	ds_read_b128 v[136:139], v234 offset:54080
	ds_read_b128 v[132:135], v234 offset:37216
	ds_read_b128 v[128:131], v234 offset:54112
	s_cbranch_vccnz .LBB0_400
	v_add_u32_e32 v244, s88, v240
	v_add_u32_e32 v245, 0xffffff80, v244
	v_cmp_gt_i32_e32 vcc, v203, v245
	v_add_u32_e32 v244, 0xffffff60, v244
	s_nop 0
	v_cndmask_b32_e32 v246, v48, v235, vcc
	v_cmp_lt_i32_e32 vcc, v203, v245
	s_nop 1
	v_cndmask_b32_e32 v48, v246, v48, vcc
	v_cndmask_b32_e32 v49, v235, v49, vcc
	v_cmp_le_i32_e32 vcc, v204, v245
	s_nop 1
	v_cndmask_b32_e32 v50, v235, v50, vcc
	v_cmp_le_i32_e32 vcc, v205, v245
	s_nop 1
	v_cndmask_b32_e32 v51, v235, v51, vcc
	v_cmp_le_i32_e32 vcc, v206, v245
	s_nop 1
	v_cndmask_b32_e32 v52, v235, v52, vcc
	v_cmp_le_i32_e32 vcc, v207, v245
	s_nop 1
	v_cndmask_b32_e32 v53, v235, v53, vcc
	v_cmp_le_i32_e32 vcc, v208, v245
	s_nop 1
	v_cndmask_b32_e32 v54, v235, v54, vcc
	v_cmp_le_i32_e32 vcc, v209, v245
	s_nop 1
	v_cndmask_b32_e32 v55, v235, v55, vcc
	v_cmp_le_i32_e32 vcc, v210, v245
	s_nop 1
	v_cndmask_b32_e32 v56, v235, v56, vcc
	v_cmp_le_i32_e32 vcc, v211, v245
	s_nop 1
	v_cndmask_b32_e32 v57, v235, v57, vcc
	v_cmp_le_i32_e32 vcc, v212, v245
	s_nop 1
	v_cndmask_b32_e32 v58, v235, v58, vcc
	v_cmp_le_i32_e32 vcc, v213, v245
	s_nop 1
	v_cndmask_b32_e32 v59, v235, v59, vcc
	v_cmp_le_i32_e32 vcc, v214, v245
	s_nop 1
	v_cndmask_b32_e32 v60, v235, v60, vcc
	v_cmp_le_i32_e32 vcc, v216, v245
	s_nop 1
	v_cndmask_b32_e32 v61, v235, v61, vcc
	v_cmp_le_i32_e32 vcc, v217, v245
	s_nop 1
	v_cndmask_b32_e32 v62, v235, v62, vcc
	v_cmp_le_i32_e32 vcc, v218, v245
	s_nop 1
	v_cndmask_b32_e32 v63, v235, v63, vcc
	v_cmp_le_i32_e32 vcc, v203, v244
	s_nop 1
	v_cndmask_b32_e32 v32, v235, v32, vcc
	v_cmp_lt_i32_e32 vcc, v203, v244
	s_nop 1
	v_cndmask_b32_e32 v33, v235, v33, vcc
	v_cmp_le_i32_e32 vcc, v204, v244
	s_nop 1
	v_cndmask_b32_e32 v34, v235, v34, vcc
	v_cmp_le_i32_e32 vcc, v205, v244
	s_nop 1
	v_cndmask_b32_e32 v35, v235, v35, vcc
	v_cmp_le_i32_e32 vcc, v206, v244
	s_nop 1
	v_cndmask_b32_e32 v36, v235, v36, vcc
	v_cmp_le_i32_e32 vcc, v207, v244
	s_nop 1
	v_cndmask_b32_e32 v37, v235, v37, vcc
	v_cmp_le_i32_e32 vcc, v208, v244
	s_nop 1
	v_cndmask_b32_e32 v38, v235, v38, vcc
	v_cmp_le_i32_e32 vcc, v209, v244
	s_nop 1
	v_cndmask_b32_e32 v39, v235, v39, vcc
	v_cmp_le_i32_e32 vcc, v210, v244
	s_nop 1
	v_cndmask_b32_e32 v40, v235, v40, vcc
	v_cmp_le_i32_e32 vcc, v211, v244
	s_nop 1
	v_cndmask_b32_e32 v41, v235, v41, vcc
	v_cmp_le_i32_e32 vcc, v212, v244
	s_nop 1
	v_cndmask_b32_e32 v42, v235, v42, vcc
	v_cmp_le_i32_e32 vcc, v213, v244
	s_nop 1
	v_cndmask_b32_e32 v43, v235, v43, vcc
	v_cmp_le_i32_e32 vcc, v214, v244
	s_nop 1
	v_cndmask_b32_e32 v44, v235, v44, vcc
	v_cmp_le_i32_e32 vcc, v216, v244
	s_nop 1
	v_cndmask_b32_e32 v45, v235, v45, vcc
	v_cmp_le_i32_e32 vcc, v217, v244
	s_nop 1
	v_cndmask_b32_e32 v46, v235, v46, vcc
	v_cmp_le_i32_e32 vcc, v218, v244
	s_nop 1
	v_cndmask_b32_e32 v47, v235, v47, vcc

.Lp3lz_skip3:
	v_exp_f32_e32 v63, v48
	v_cvt_pk_bf16_f32 v48, v197, v246
	v_cvt_pk_bf16_f32 v49, v247, v248
	v_cvt_pk_bf16_f32 v50, v52, v53
	v_cvt_pk_bf16_f32 v51, v54, v55
	v_fmac_f32_e32 v197, v162, v244
	v_sub_f32_e32 v32, v32, v245
	v_mfma_f32_32x32x16_bf16 v[0:15], v[156:159], v[48:51], v[0:15]
	v_mfma_f32_32x32x16_bf16 v[16:31], v[152:155], v[48:51], v[16:31]
	v_cvt_pk_bf16_f32 v48, v56, v57
	v_cvt_pk_bf16_f32 v49, v58, v59
	v_cvt_pk_bf16_f32 v50, v60, v61
	v_cvt_pk_bf16_f32 v51, v62, v63
	s_nop 1
	v_mfma_f32_32x32x16_bf16 v[0:15], v[144:147], v[48:51], v[0:15]
	v_mfma_f32_32x32x16_bf16 v[16:31], v[148:151], v[48:51], v[16:31]
	v_add_f32_e32 v48, v246, v197
	v_exp_f32_e32 v49, v32
	v_sub_f32_e32 v32, v33, v245
	v_add_f32_e32 v48, v247, v48
	v_exp_f32_e32 v50, v32
	v_sub_f32_e32 v32, v34, v245
	v_add_f32_e32 v48, v248, v48
	v_exp_f32_e32 v51, v32
	v_sub_f32_e32 v32, v35, v245
	v_add_f32_e32 v48, v52, v48
	v_exp_f32_e32 v52, v32
	v_sub_f32_e32 v32, v36, v245
	v_exp_f32_e32 v36, v32
	v_sub_f32_e32 v32, v37, v245
	v_exp_f32_e32 v37, v32
	v_sub_f32_e32 v32, v38, v245
	v_exp_f32_e32 v38, v32
	v_sub_f32_e32 v32, v39, v245
	v_exp_f32_e32 v39, v32
	v_sub_f32_e32 v32, v40, v245
	v_exp_f32_e32 v40, v32
	v_sub_f32_e32 v32, v41, v245
	v_exp_f32_e32 v41, v32
	v_sub_f32_e32 v32, v42, v245
	v_exp_f32_e32 v42, v32
	v_sub_f32_e32 v32, v43, v245
	v_exp_f32_e32 v43, v32
	v_sub_f32_e32 v32, v44, v245
	v_exp_f32_e32 v44, v32
	v_sub_f32_e32 v32, v45, v245
	v_add_f32_e32 v48, v53, v48
	v_exp_f32_e32 v45, v32
	v_sub_f32_e32 v32, v46, v245
	v_add_f32_e32 v48, v54, v48
	v_exp_f32_e32 v46, v32
	v_sub_f32_e32 v32, v47, v245
	v_add_f32_e32 v48, v55, v48
	v_exp_f32_e32 v47, v32
	v_cvt_pk_bf16_f32 v32, v49, v50
	v_cvt_pk_bf16_f32 v33, v51, v52
	v_cvt_pk_bf16_f32 v34, v36, v37
	v_cvt_pk_bf16_f32 v35, v38, v39
	v_add_f32_e32 v48, v56, v48
	v_add_f32_e32 v48, v57, v48
	v_mfma_f32_32x32x16_bf16 v[0:15], v[140:143], v[32:35], v[0:15]
	v_add_f32_e32 v48, v58, v48
	v_add_f32_e32 v48, v59, v48
	v_add_f32_e32 v48, v60, v48
	v_add_f32_e32 v48, v61, v48
	v_add_f32_e32 v48, v62, v48
	v_add_f32_e32 v48, v63, v48
	v_mov_b32_e32 v197, v245
	v_mfma_f32_32x32x16_bf16 v[16:31], v[136:139], v[32:35], v[16:31]
	ds_read_b128 v[152:155], v233 offset:27648
	ds_read_b128 v[156:159], v233 offset:32256
	ds_read_b128 v[148:151], v233 offset:32352
	v_cvt_pk_bf16_f32 v32, v40, v41
	v_cvt_pk_bf16_f32 v33, v42, v43
	v_cvt_pk_bf16_f32 v34, v44, v45
	v_cvt_pk_bf16_f32 v35, v46, v47
	s_nop 1
	v_mfma_f32_32x32x16_bf16 v[0:15], v[132:135], v[32:35], v[0:15]
	v_mfma_f32_32x32x16_bf16 v[16:31], v[128:131], v[32:35], v[16:31]
	v_add_f32_e32 v32, v49, v48
	v_add_f32_e32 v32, v50, v32
	v_add_f32_e32 v32, v51, v32
	v_add_f32_e32 v32, v52, v32
	v_add_f32_e32 v32, v36, v32
	v_add_f32_e32 v32, v37, v32
	v_add_f32_e32 v32, v38, v32
	v_add_f32_e32 v32, v39, v32
	v_add_f32_e32 v32, v40, v32
	v_add_f32_e32 v32, v41, v32
	v_add_f32_e32 v32, v42, v32
	v_add_f32_e32 v32, v43, v32
	v_add_f32_e32 v32, v44, v32
	v_add_f32_e32 v32, v45, v32
	v_add_f32_e32 v32, v46, v32
	v_add_f32_e32 v162, v47, v32
	s_cmp_lt_u32 s58, 6
	s_cbranch_scc1 .LBB0_404
.LBB0_401:
	ds_read_b128 v[128:131], v233 offset:27680
	ds_read_b128 v[132:135], v233 offset:32288
	s_and_b64 vcc, exec, s[0:1]
	s_waitcnt lgkmcnt(2)
	v_mfma_f32_32x32x16_bf16 v[48:63], v[152:155], v[108:111], 0
	v_mfma_f32_32x32x16_bf16 v[32:47], v[156:159], v[108:111], 0
	s_waitcnt lgkmcnt(1)
	v_mfma_f32_32x32x16_bf16 v[48:63], v[128:131], v[104:107], v[48:63]
	s_waitcnt lgkmcnt(0)
	v_mfma_f32_32x32x16_bf16 v[32:47], v[132:135], v[104:107], v[32:47]
	ds_read_b128 v[104:107], v233 offset:27712
	ds_read_b128 v[108:111], v233 offset:27744
	s_waitcnt lgkmcnt(1)
	v_mfma_f32_32x32x16_bf16 v[48:63], v[104:107], v[100:103], v[48:63]
	ds_read_b128 v[104:107], v233 offset:32320
	s_waitcnt lgkmcnt(0)
	v_mfma_f32_32x32x16_bf16 v[32:47], v[104:107], v[100:103], v[32:47]
	v_mfma_f32_32x32x16_bf16 v[48:63], v[108:111], v[96:99], v[48:63]
	ds_read_b128 v[144:147], v234 offset:37248
	ds_read_b128 v[132:135], v234 offset:37280
	ds_read_b128 v[140:143], v234 offset:54144
	ds_read_b128 v[136:139], v234 offset:54176
	ds_read_b128 v[128:131], v234 offset:37312
	ds_read_b128 v[104:107], v234 offset:37344
	ds_read_b128 v[108:111], v234 offset:54208
	ds_read_b128 v[100:103], v234 offset:54240
	v_mfma_f32_32x32x16_bf16 v[32:47], v[148:151], v[96:99], v[32:47]
	s_cbranch_vccnz .LBB0_403
	v_add_u32_e32 v96, s88, v240
	v_add_u32_e32 v97, 0xffffff40, v96
	v_cmp_gt_i32_e32 vcc, v203, v97
	v_add_u32_e32 v96, 0xffffff20, v96
	s_nop 0
	v_cndmask_b32_e32 v98, v48, v235, vcc
	v_cmp_lt_i32_e32 vcc, v203, v97
	s_nop 1
	v_cndmask_b32_e32 v48, v98, v48, vcc
	v_cndmask_b32_e32 v49, v235, v49, vcc
	v_cmp_le_i32_e32 vcc, v204, v97
	s_nop 1
	v_cndmask_b32_e32 v50, v235, v50, vcc
	v_cmp_le_i32_e32 vcc, v205, v97
	s_nop 1
	v_cndmask_b32_e32 v51, v235, v51, vcc
	v_cmp_le_i32_e32 vcc, v206, v97
	s_nop 1
	v_cndmask_b32_e32 v52, v235, v52, vcc
	v_cmp_le_i32_e32 vcc, v207, v97
	s_nop 1
	v_cndmask_b32_e32 v53, v235, v53, vcc
	v_cmp_le_i32_e32 vcc, v208, v97
	s_nop 1
	v_cndmask_b32_e32 v54, v235, v54, vcc
	v_cmp_le_i32_e32 vcc, v209, v97
	s_nop 1
	v_cndmask_b32_e32 v55, v235, v55, vcc
	v_cmp_le_i32_e32 vcc, v210, v97
	s_nop 1
	v_cndmask_b32_e32 v56, v235, v56, vcc
	v_cmp_le_i32_e32 vcc, v211, v97
	s_nop 1
	v_cndmask_b32_e32 v57, v235, v57, vcc
	v_cmp_le_i32_e32 vcc, v212, v97
	s_nop 1
	v_cndmask_b32_e32 v58, v235, v58, vcc
	v_cmp_le_i32_e32 vcc, v213, v97
	s_nop 1
	v_cndmask_b32_e32 v59, v235, v59, vcc
	v_cmp_le_i32_e32 vcc, v214, v97
	s_nop 1
	v_cndmask_b32_e32 v60, v235, v60, vcc
	v_cmp_le_i32_e32 vcc, v216, v97
	s_nop 1
	v_cndmask_b32_e32 v61, v235, v61, vcc
	v_cmp_le_i32_e32 vcc, v217, v97
	s_nop 1
	v_cndmask_b32_e32 v62, v235, v62, vcc
	v_cmp_le_i32_e32 vcc, v218, v97
	s_nop 1
	v_cndmask_b32_e32 v63, v235, v63, vcc
	v_cmp_le_i32_e32 vcc, v203, v96
	s_nop 1
	v_cndmask_b32_e32 v32, v235, v32, vcc
	v_cmp_lt_i32_e32 vcc, v203, v96
	s_nop 1
	v_cndmask_b32_e32 v33, v235, v33, vcc
	v_cmp_le_i32_e32 vcc, v204, v96
	s_nop 1
	v_cndmask_b32_e32 v34, v235, v34, vcc
	v_cmp_le_i32_e32 vcc, v205, v96
	s_nop 1
	v_cndmask_b32_e32 v35, v235, v35, vcc
	v_cmp_le_i32_e32 vcc, v206, v96
	s_nop 1
	v_cndmask_b32_e32 v36, v235, v36, vcc
	v_cmp_le_i32_e32 vcc, v207, v96
	s_nop 1
	v_cndmask_b32_e32 v37, v235, v37, vcc
	v_cmp_le_i32_e32 vcc, v208, v96
	s_nop 1
	v_cndmask_b32_e32 v38, v235, v38, vcc
	v_cmp_le_i32_e32 vcc, v209, v96
	s_nop 1
	v_cndmask_b32_e32 v39, v235, v39, vcc
	v_cmp_le_i32_e32 vcc, v210, v96
	s_nop 1
	v_cndmask_b32_e32 v40, v235, v40, vcc
	v_cmp_le_i32_e32 vcc, v211, v96
	s_nop 1
	v_cndmask_b32_e32 v41, v235, v41, vcc
	v_cmp_le_i32_e32 vcc, v212, v96
	s_nop 1
	v_cndmask_b32_e32 v42, v235, v42, vcc
	v_cmp_le_i32_e32 vcc, v213, v96
	s_nop 1
	v_cndmask_b32_e32 v43, v235, v43, vcc
	v_cmp_le_i32_e32 vcc, v214, v96
	s_nop 1
	v_cndmask_b32_e32 v44, v235, v44, vcc
	v_cmp_le_i32_e32 vcc, v216, v96
	s_nop 1
	v_cndmask_b32_e32 v45, v235, v45, vcc
	v_cmp_le_i32_e32 vcc, v217, v96
	s_nop 1
	v_cndmask_b32_e32 v46, v235, v46, vcc
	v_cmp_le_i32_e32 vcc, v218, v96
	s_nop 1
	v_cndmask_b32_e32 v47, v235, v47, vcc
